# grid barrier: XCD leaders post a non-returning add and every workgroup polls the arrival count against nx*(gen+1); removes the returning top-level atomic and the separate release word (one round trip
# baseline (speedup 1.0000x reference)
; __device__ __forceinline__ unsigned xb_ld(unsigned* p)              { return __hip_atomic_load(p, __ATOMIC_RELAXED, __HIP_MEMORY_SCOPE_AGENT); }
; __device__ __forceinline__ unsigned xb_add(unsigned* p, unsigned v) { return __hip_atomic_fetch_add(p, v, __ATOMIC_RELAXED, __HIP_MEMORY_SCOPE_AGENT); }
; #define XB_SPIN(cond, bar) do { unsigned _sp = 0; while (cond) { __builtin_amdgcn_s_sleep(1); \
;     if ((++_sp & 255u) == 0u) { if (xb_ld(&(bar)[XB_TMO])) break; if (_sp > XB_SPIN_CAP) { atomicAdd(&(bar)[XB_TMO], 1u); break; } } } } while (0)
; __device__ __forceinline__ void xcd_barrier(const XcdBarrier& b) {
;     ...
;         const unsigned old = xb_add(&bar[XB_XSUB(b.x)], 1u);
;         const unsigned gen = old / nloc;
;         if (old + 1u == (gen + 1u) * nloc) {
;             __builtin_amdgcn_fence(__ATOMIC_RELEASE, "agent");
;             asm volatile("s_waitcnt vmcnt(0)" ::: "memory");
;             const unsigned og = xb_add(&bar[XB_TOP], 1u);
;             const unsigned tg = og / nx;
;             if (og + 1u == (tg + 1u) * nx) xb_add(&bar[XB_TOPGEN], 1u);
;             else XB_SPIN(xb_ld(&bar[XB_TOPGEN]) == tg, bar);
;             __builtin_amdgcn_fence(__ATOMIC_ACQUIRE, "agent");
;             xb_add(&bar[XB_XGEN(b.x)], 1u);
;             asm volatile("s_waitcnt vmcnt(0)" ::: "memory");
;         } else {
;             XB_SPIN(xb_ld(&bar[XB_XGEN(b.x)]) == gen, bar);
;             __builtin_amdgcn_fence(__ATOMIC_ACQUIRE, "agent");
;             asm volatile("s_waitcnt vmcnt(0)" ::: "memory");
;         }
.LBB0_81:
	s_or_b64 exec, exec, s[8:9]
	v_cvt_f32_u32_e32 v4, v2
	s_waitcnt vmcnt(0)
	v_readfirstlane_b32 s2, v3
	v_sub_u32_e32 v3, 0, v2
	v_rcp_iflag_f32_e32 v4, v4
	v_add_u32_e32 v5, s2, v1
	v_mul_f32_e32 v4, 0x4f7ffffe, v4
	v_cvt_u32_f32_e32 v4, v4
	v_mul_lo_u32 v1, v3, v4
	v_mul_hi_u32 v1, v4, v1
	v_add_u32_e32 v1, v4, v1
	v_mul_hi_u32 v1, v5, v1
	v_mul_lo_u32 v3, v1, v2
	v_sub_u32_e32 v3, v5, v3
	v_add_u32_e32 v4, 1, v1
	v_cmp_ge_u32_e32 vcc, v3, v2
	s_nop 1
	v_cndmask_b32_e32 v1, v1, v4, vcc
	v_sub_u32_e32 v4, v3, v2
	v_cndmask_b32_e32 v3, v3, v4, vcc
	v_add_u32_e32 v4, 1, v1
	v_cmp_ge_u32_e32 vcc, v3, v2
	v_add_u32_e32 v3, 1, v5
	s_nop 0
	v_cndmask_b32_e32 v1, v1, v4, vcc
	v_mul_lo_u32 v4, v2, v1
	v_add_u32_e32 v2, v4, v2
	v_cmp_ne_u32_e32 vcc, v3, v2
	s_waitcnt lgkmcnt(0)
	v_add_u32_e32 v4, 1, v1
	v_mul_lo_u32 v4, v4, v0
	v_mov_b32_e32 v2, 0x583000
	v_readfirstlane_b32 s8, v4
	s_cbranch_vccnz .Lgb_poll_0
	buffer_wbl2 sc1
	v_mov_b32_e32 v3, 1
	s_waitcnt vmcnt(0)
	global_atomic_add v2, v3, s[72:73] offset:1024
.Lgb_poll_0:
	s_mov_b32 s3, 0
.Lgb_spin_0:
	global_load_dword v3, v2, s[72:73] offset:1024 sc1
	s_waitcnt vmcnt(0)
	v_readfirstlane_b32 s2, v3
	s_sub_u32 s2, s2, s8
	s_cmp_ge_i32 s2, 0
	s_cbranch_scc1 .Lgb_done_0
	s_sleep 1
	s_add_u32 s3, s3, 1
	s_cmp_lt_u32 s3, 0x40000
	s_cbranch_scc1 .Lgb_spin_0

; __device__ __forceinline__ unsigned xb_ld(unsigned* p)              { return __hip_atomic_load(p, __ATOMIC_RELAXED, __HIP_MEMORY_SCOPE_AGENT); }
; __device__ __forceinline__ unsigned xb_add(unsigned* p, unsigned v) { return __hip_atomic_fetch_add(p, v, __ATOMIC_RELAXED, __HIP_MEMORY_SCOPE_AGENT); }
; #define XB_SPIN(cond, bar) do { unsigned _sp = 0; while (cond) { __builtin_amdgcn_s_sleep(1); \
;     if ((++_sp & 255u) == 0u) { if (xb_ld(&(bar)[XB_TMO])) break; if (_sp > XB_SPIN_CAP) { atomicAdd(&(bar)[XB_TMO], 1u); break; } } } } while (0)
;     __host__ __device__ bool next(int i, Unit& u) const {
;         const long L = (long)i * G + c; if (L >= nwg) return false;
;         int wgid = (int)L; { const int q = nwg / NXCD, r = nwg % NXCD, xcd = wgid % NXCD, off = wgid / NXCD; wgid = (xcd < r ? xcd * (q + 1) : r * (q + 1) + (xcd - r) * q) + off; }
; __device__ __forceinline__ void xcd_barrier(const XcdBarrier& b) {
;     ...
;         const unsigned old = xb_add(&bar[XB_XSUB(b.x)], 1u);
;         const unsigned gen = old / nloc;
;         if (old + 1u == (gen + 1u) * nloc) {
;             __builtin_amdgcn_fence(__ATOMIC_RELEASE, "agent");
;             asm volatile("s_waitcnt vmcnt(0)" ::: "memory");
;             const unsigned og = xb_add(&bar[XB_TOP], 1u);
;             const unsigned tg = og / nx;
;             if (og + 1u == (tg + 1u) * nx) xb_add(&bar[XB_TOPGEN], 1u);
;             else XB_SPIN(xb_ld(&bar[XB_TOPGEN]) == tg, bar);
;             __builtin_amdgcn_fence(__ATOMIC_ACQUIRE, "agent");
;             xb_add(&bar[XB_XGEN(b.x)], 1u);
;             asm volatile("s_waitcnt vmcnt(0)" ::: "memory");
;         } else {
;             XB_SPIN(xb_ld(&bar[XB_XGEN(b.x)]) == gen, bar);
;             __builtin_amdgcn_fence(__ATOMIC_ACQUIRE, "agent");
;             asm volatile("s_waitcnt vmcnt(0)" ::: "memory");
;         }
;     }
;     __syncthreads();
.Lgb_done_1:
	s_branch .LBB0_349
.LBB0_341:
	s_branch .LBB0_261
.LBB0_349:
	s_or_b64 exec, exec, s[0:1]
	s_cmpk_lt_i32 s86, 0x100
	v_lshrrev_b32_e32 v175, 2, v152
	s_cselect_b64 s[0:1], -1, 0
	s_cmpk_gt_i32 s86, 0xff
	v_readfirstlane_b32 s8, v152
	s_waitcnt lgkmcnt(0)
	s_barrier
	s_cbranch_scc1 .LBB0_355
	s_ashr_i32 s2, s86, 31
	s_lshr_b32 s2, s2, 29
	s_add_i32 s2, s86, s2
	s_and_b32 s3, s2, -8
	s_sub_i32 s3, s86, s3
	s_cmp_gt_i32 s3, -1
	s_cbranch_scc0 .LBB0_352
	s_lshl_b32 s6, s3, 5
	s_cbranch_execz .LBB0_353
	s_branch .LBB0_354

; __device__ __forceinline__ float log_sigmoid_f(float x) { return fminf(x, 0.f) - log1pf(expf(-fabsf(x))); }
; __device__ __forceinline__ void m1_phase(const Params& p, unsigned char* ldsg, int G) {
;     const int tid = threadIdx.x, lane = tid & 63, wave = __builtin_amdgcn_readfirstlane(tid >> 6), fr = lane & 15, fq = lane >> 4;
;     const int half = wave >> 2, hw = wave & 3, htid = tid & 255;
;     unsigned char* ws = p.ws;
;     const bf16* PROJ = (const bf16*)(ws + WS_HB); const float* GATES = (const float*)(ws + WS_GATES);
;     bf16* DCB = (bf16*)p.out; bf16* QKC = (bf16*)((unsigned char*)p.out + 32 * MiB); float* DN = (float*)(ws + WS_DN); float* GARR = (float*)(ws + WS_SC); float* AMAXARR = GARR + 1024;
;     bf16* KT = (bf16*)(ldsg + half * 40960); bf16* VT = KT + 128 * TP; float* sW = (float*)(ldsg + half * 40960 + 36864);
;     for (int r = blockIdx.x; r < NCH * NH / 2; r += G) {
;         const int c = r >> 1, h = 2 * (r & 1) + half, u = c * 4 + h, t0 = c * CL;
;         if (hw == 0) {
;             const float ig = GATES[(size_t)(t0 + lane) * 8 + h], fp = GATES[(size_t)(t0 + lane) * 8 + 4 + h];
;             const float b = wave_incl_sum(log_sigmoid_f(fp), lane);
;             const float g = __shfl(b, 63);
;             const float a = g - b + ig;
;             const float amax = wave_max(a);
;             sW[lane] = expf(a - amax);
;             if (lane == 0) { GARR[h * NCH + c] = g; AMAXARR[h * NCH + c] = amax; }
;         }
;         const int rg = htid >> 4, cgp = htid & 15, l0 = 4 * rg;
.Lgb_done_3:
	s_branch .LBB0_608
.LBB0_600:
	s_branch .LBB0_553
.LBB0_608:
	s_or_b64 exec, exec, s[0:1]
	s_add_u32 s56, s70, 0x2000000
	s_addc_u32 s57, s71, 0
	s_add_u32 s34, s72, 0x500000
	s_addc_u32 s35, s73, 0
	s_add_u32 s36, s72, 0x501000
	v_lshrrev_b32_e32 v159, 4, v153
	s_addc_u32 s37, s73, 0
	v_readfirstlane_b32 s0, v240
	s_cmpk_gt_i32 s86, 0x1ff
	v_cmp_gt_u32_e64 s[8:9], 2, v153
	v_cmp_gt_u32_e64 s[10:11], 4, v153
	v_cmp_gt_u32_e64 s[12:13], 8, v153
	v_cmp_gt_u32_e64 s[14:15], 32, v153
	v_lshlrev_b32_e32 v92, 3, v159
	v_lshlrev_b32_e32 v167, 8, v152
	v_and_b32_e32 v157, 8, v152
	s_waitcnt lgkmcnt(0)
	s_barrier
	s_cbranch_scc1 .LBB0_648
	s_ashr_i32 s2, s0, 2
	v_and_b32_e32 v64, 0x78, v230
	s_mul_i32 s1, s2, 0xa000
	v_mov_b32_e32 v67, 0
	v_lshlrev_b32_e32 v66, 1, v64
	v_and_b32_e32 v0, 56, v230
	s_add_i32 s1, s1, 0
	v_and_b32_e32 v2, 0xff, v152
	v_lshl_add_u64 v[68:69], s[56:57], 0, v[66:67]
	v_bitop3_b32 v0, v175, v0, 60 bitop3:0x6c
	v_and_b32_e32 v66, 0x100, v167
	s_and_b32 s3, s0, 3
	v_and_b32_e32 v118, 60, v175
	v_lshl_add_u32 v4, v0, 1, s1
	v_lshl_add_u64 v[0:1], s[70:71], 0, v[66:67]
	v_mov_b32_e32 v93, v67
	s_movk_i32 s0, 0x80
	v_lshlrev_b32_e32 v66, 2, v2
	v_mov_b32_e32 v3, s1
	v_lshl_add_u32 v65, v153, 2, s1
	v_lshl_add_u32 v120, v118, 2, s1
	v_lshl_or_b32 v5, s3, 5, v234
	v_lshl_add_u64 v[70:71], v[0:1], 0, v[92:93]
	v_cmp_gt_u32_e64 s[20:21], s0, v2
	s_movk_i32 s6, 0x90
	v_lshl_add_u64 v[0:1], s[72:73], 0, v[66:67]
	s_mov_b64 s[0:1], 0x480000
	v_mad_u32_u24 v93, v2, s6, v3
	v_lshl_add_u64 v[72:73], v[0:1], 0, s[0:1]
	v_mad_u32_u24 v1, v5, s6, v3
	v_bitop3_b32 v2, v5, v92, 40 bitop3:0x6c
	v_lshl_add_u32 v121, v2, 1, v1
	v_or_b32_e32 v2, 32, v92
	v_bitop3_b32 v7, v5, v2, 40 bitop3:0x6c
	v_or_b32_e32 v5, 16, v5
	v_lshl_add_u32 v122, v7, 1, v1
	v_add_u32_e32 v1, 0x900, v1
	v_bitop3_b32 v7, v5, v92, 56 bitop3:0x6c
	v_bitop3_b32 v2, v5, v2, 56 bitop3:0x6c
	v_lshl_add_u32 v123, v7, 1, v1
	v_lshl_add_u32 v124, v2, 1, v1
	v_mad_u32_u24 v1, v234, s6, v3
	v_bitop3_b32 v2, v92, v152, 8 bitop3:0x78
	v_lshlrev_b32_e32 v6, 7, v152
	v_lshl_add_u32 v125, v2, 1, v1
	v_bitop3_b32 v2, v92, v157, 32 bitop3:0x36
	v_lshl_add_u32 v126, v2, 1, v1
	v_and_b32_e32 v2, 0x700, v6
	v_lshl_or_b32 v127, s3, 12, v2
	v_or_b32_e32 v2, 16, v234
	v_bitop3_b32 v3, v234, 24, 16 bitop3:0xc8
	v_bitop3_b32 v2, v92, v2, 24 bitop3:0x78
	v_bitop3_b32 v3, v92, v3, 32 bitop3:0x36
	v_add_u32_e32 v5, 0x900, v1
	v_lshlrev_b32_e32 v2, 1, v2
	v_lshlrev_b32_e32 v3, 1, v3
	v_add_u32_e32 v129, v5, v2
	v_add_u32_e32 v130, v5, v3
	v_or_b32_e32 v5, 32, v234
	v_bitop3_b32 v6, v234, 40, 32 bitop3:0xc8
	v_bitop3_b32 v5, v92, v5, 40 bitop3:0x78
	v_bitop3_b32 v6, v92, v6, 32 bitop3:0x36
	v_add_u32_e32 v7, 0x1200, v1
	v_lshlrev_b32_e32 v5, 1, v5
	v_lshlrev_b32_e32 v6, 1, v6
	v_add_u32_e32 v131, v7, v5
	v_add_u32_e32 v132, v7, v6
	v_or_b32_e32 v7, 48, v234
	v_bitop3_b32 v8, v234, 56, 48 bitop3:0xc8
	v_bitop3_b32 v7, v92, v7, 56 bitop3:0x78
	v_bitop3_b32 v8, v92, v8, 32 bitop3:0x36
	v_mul_u32_u24_e32 v0, 0x90, v64
	v_add_u32_e32 v9, 0x1b00, v1
	v_lshlrev_b32_e32 v7, 1, v7
	v_lshlrev_b32_e32 v8, 1, v8
	v_add_u32_e32 v133, v9, v7
	v_add_u32_e32 v134, v9, v8
	v_add_u32_e32 v9, 0x2d00, v1
	v_add_u32_e32 v142, v4, v0
	v_mbcnt_lo_u32_b32 v0, -1, 0
	s_cmp_eq_u32 s3, 0
	v_add_u32_e32 v135, v9, v2
	v_add_u32_e32 v2, 0x3600, v1
	v_add_u32_e32 v1, 0x3f00, v1
	v_mbcnt_hi_u32_b32 v144, -1, v0
	v_bfrev_b32_e32 v0, 0.5
	s_cselect_b64 s[4:5], -1, 0
	v_cmp_eq_u32_e64 s[16:17], 0, v153
	v_cmp_gt_u32_e64 s[18:19], 16, v153
	v_or_b32_e32 v119, 0x200, v64
	v_or_b32_e32 v128, 0x800, v127
	v_add_u32_e32 v136, v9, v3
	v_add_u32_e32 v137, v2, v5
	v_add_u32_e32 v138, v2, v6
	v_add_u32_e32 v139, v1, v7
	v_add_u32_e32 v140, v1, v8
	s_mov_b32 s3, 0xbfb8aa3b
	v_mov_b32_e32 v141, 0x3ecc95a3
	s_mov_b32 s33, 0x3f317218
	s_mov_b32 s43, 0x33800000
	s_mov_b32 s46, 0x3fb8aa3b
	s_mov_b32 s47, 0xc2ce8ed0
	s_mov_b32 s62, 0x42b17218
	s_movk_i32 s63, 0x1600
	s_mov_b32 s64, 0xffff0000
	s_mov_b64 s[6:7], 0x1000
	s_mov_b64 s[38:39], 0x2000
	s_movk_i32 s65, 0x2000
	s_mov_b64 s[40:41], 0x3000
	s_movk_i32 s80, 0x3000
	s_movk_i32 s81, 0x7fff
	s_mov_b32 s42, 0x3db504f3
	v_lshlrev_b32_e32 v66, 1, v64
	v_mov_b32_e32 v143, 0x7f800000
	v_lshl_or_b32 v145, v144, 2, v0
	v_mov_b32_e32 v146, 1
	s_mov_b32 s82, s86
	s_branch .LBB0_611

; __device__ __forceinline__ unsigned xb_ld(unsigned* p)              { return __hip_atomic_load(p, __ATOMIC_RELAXED, __HIP_MEMORY_SCOPE_AGENT); }
; __device__ __forceinline__ unsigned xb_add(unsigned* p, unsigned v) { return __hip_atomic_fetch_add(p, v, __ATOMIC_RELAXED, __HIP_MEMORY_SCOPE_AGENT); }
; #define XB_SPIN(cond, bar) do { unsigned _sp = 0; while (cond) { __builtin_amdgcn_s_sleep(1); \
;     if ((++_sp & 255u) == 0u) { if (xb_ld(&(bar)[XB_TMO])) break; if (_sp > XB_SPIN_CAP) { atomicAdd(&(bar)[XB_TMO], 1u); break; } } } } while (0)
; __device__ __forceinline__ void xcd_barrier(const XcdBarrier& b) {
;     ...
;         const unsigned old = xb_add(&bar[XB_XSUB(b.x)], 1u);
;         const unsigned gen = old / nloc;
;         if (old + 1u == (gen + 1u) * nloc) {
;             __builtin_amdgcn_fence(__ATOMIC_RELEASE, "agent");
;             asm volatile("s_waitcnt vmcnt(0)" ::: "memory");
;             const unsigned og = xb_add(&bar[XB_TOP], 1u);
;             const unsigned tg = og / nx;
;             if (og + 1u == (tg + 1u) * nx) xb_add(&bar[XB_TOPGEN], 1u);
;             else XB_SPIN(xb_ld(&bar[XB_TOPGEN]) == tg, bar);
;             __builtin_amdgcn_fence(__ATOMIC_ACQUIRE, "agent");
;             xb_add(&bar[XB_XGEN(b.x)], 1u);
;             asm volatile("s_waitcnt vmcnt(0)" ::: "memory");
;         } else {
;             XB_SPIN(xb_ld(&bar[XB_XGEN(b.x)]) == gen, bar);
;             __builtin_amdgcn_fence(__ATOMIC_ACQUIRE, "agent");
;             asm volatile("s_waitcnt vmcnt(0)" ::: "memory");
;         }
.LBB0_1080:
	s_or_b64 exec, exec, s[10:11]
	v_cvt_f32_u32_e32 v4, v2
	s_waitcnt vmcnt(0)
	v_readfirstlane_b32 s2, v3
	v_sub_u32_e32 v3, 0, v2
	v_rcp_iflag_f32_e32 v4, v4
	v_add_u32_e32 v5, s2, v1
	v_mul_f32_e32 v4, 0x4f7ffffe, v4
	v_cvt_u32_f32_e32 v4, v4
	v_mul_lo_u32 v1, v3, v4
	v_mul_hi_u32 v1, v4, v1
	v_add_u32_e32 v1, v4, v1
	v_mul_hi_u32 v1, v5, v1
	v_mul_lo_u32 v3, v1, v2
	v_sub_u32_e32 v3, v5, v3
	v_add_u32_e32 v4, 1, v1
	v_cmp_ge_u32_e32 vcc, v3, v2
	s_nop 1
	v_cndmask_b32_e32 v1, v1, v4, vcc
	v_sub_u32_e32 v4, v3, v2
	v_cndmask_b32_e32 v3, v3, v4, vcc
	v_add_u32_e32 v4, 1, v1
	v_cmp_ge_u32_e32 vcc, v3, v2
	v_add_u32_e32 v3, 1, v5
	s_nop 0
	v_cndmask_b32_e32 v1, v1, v4, vcc
	v_mul_lo_u32 v4, v2, v1
	v_add_u32_e32 v2, v4, v2
	v_cmp_ne_u32_e32 vcc, v3, v2
	s_waitcnt lgkmcnt(0)
	v_add_u32_e32 v4, 1, v1
	v_mul_lo_u32 v4, v4, v0
	v_mov_b32_e32 v2, 0x583000
	v_readfirstlane_b32 s8, v4
	s_cbranch_vccnz .Lgb_poll_5
	buffer_wbl2 sc1
	v_mov_b32_e32 v3, 1
	s_waitcnt vmcnt(0)
	global_atomic_add v2, v3, s[72:73] offset:1024
